# PREP work queue: thread 0 no longer waits for the next-item atomic at item entry; result picked up at the loop latch (on top of v046)
# baseline (speedup 1.0000x reference)
; __global__ void __launch_bounds__(NTHR, 2) fwd(Args a_unused) {
;     ...
;                 for (;;) {
;                     if (tid == 0) qslot[0] = qnext;
;                     __syncthreads();
;                     const int it = (int)qslot[0];
;                     __syncthreads();
;                     if (it >= 576 + 288 + 576) break;
;                     if (tid == 0) qnext = __hip_atomic_fetch_add(qctr, 1u, __ATOMIC_RELAXED, __HIP_MEMORY_SCOPE_AGENT);
.LBB0_508:
	s_and_saveexec_b64 s[0:1], s[20:21]
	s_cbranch_execz .Lpop_fin
	v_readfirstlane_b32 s2, v250
	s_nop 1
	v_add_u32_e32 v181, s2, v249
.Lpop_fin:
	s_or_b64 exec, exec, s[0:1]
	v_readlane_b32 s0, v255, 0
	v_readlane_b32 s1, v255, 1
	s_andn2_b64 vcc, exec, s[0:1]
	s_cbranch_vccz .LBB0_853
.LBB0_509:
	s_and_saveexec_b64 s[0:1], s[20:21]
	v_mov_b32_e32 v0, s17
	ds_write_b32 v0, v181
	s_or_b64 exec, exec, s[0:1]
	v_mov_b32_e32 v0, s17
	s_waitcnt lgkmcnt(0)
	s_barrier
	ds_read_b32 v0, v0
	s_movk_i32 s0, 0x59f
	s_waitcnt lgkmcnt(0)
	s_barrier
	v_cmp_lt_i32_e64 s[0:1], s0, v0
	v_readfirstlane_b32 s9, v0
	s_nop 0
	v_writelane_b32 v255, s0, 0
	s_and_b64 vcc, exec, s[0:1]
	s_nop 0
	v_writelane_b32 v255, s1, 1
	s_cbranch_vccnz .LBB0_508
	s_and_saveexec_b64 s[0:1], s[20:21]
	s_cbranch_execz .LBB0_516
	s_mov_b64 s[4:5], exec
	v_mbcnt_lo_u32_b32 v0, s4, 0
	v_mbcnt_hi_u32_b32 v0, s5, v0
	v_cmp_eq_u32_e32 vcc, 0, v0
	s_and_saveexec_b64 s[2:3], vcc
	s_cbranch_execz .LBB0_515
	s_bcnt1_i32_b64 s4, s[4:5]
	v_mov_b32_e32 v2, s4
	v_readlane_b32 s4, v254, 19
	v_readlane_b32 s5, v254, 20
	s_nop 4
	global_atomic_add v250, v1, v2, s[4:5] sc0
.LBB0_515:
	s_or_b64 exec, exec, s[2:3]
	v_mov_b32_e32 v249, v0
